# v095 + P1 K-loop load segments: fragment ds_reads paced in groups of 2 with the address math and stage loads spread between them
# baseline (speedup 1.0000x reference)
; #define PG8_STAGE(bufoff, gbase, voff) do { _Pragma("unroll") for (int _i = 0; _i < 2; ++_i) \
;         __builtin_amdgcn_global_load_lds((const unsigned*)((const char*)(gbase) + (voff)[_i]), (PG8_LAS unsigned*)(lds + (bufoff) + ldsw + _i * 8192), 16, 0, 0); } while (0)
; #define PG8_LDA(dst, b, h) do { _Pragma("unroll") for (int m = 0; m < 4; ++m) _Pragma("unroll") for (int k = 0; k < 2; ++k) dst[m][k] = *(const PG8_LAS bf16x8*)(lds + PG8_SA(b, h) + aoff + m * 2048 + k * 1024); } while (0)
; #define PG8_LDB(dst, b, h) do { _Pragma("unroll") for (int n = 0; n < 2; ++n) _Pragma("unroll") for (int k = 0; k < 2; ++k) dst[n][k] = *(const PG8_LAS bf16x8*)(lds + PG8_SB(b, h) + boff + n * 2048 + k * 1024); } while (0)
; #define PG8_MMA(ai, bj, At, Bt) do { __builtin_amdgcn_s_setprio(1); _Pragma("unroll") for (int m = 0; m < 4; ++m) _Pragma("unroll") for (int n = 0; n < 2; ++n) _Pragma("unroll") for (int k = 0; k < 2; ++k) \
;         acc[ai][bj][m][n] = __builtin_amdgcn_mfma_f32_16x16x32_bf16(Bt[n][k], At[m][k], acc[ai][bj][m][n], 0, 0, 0); __builtin_amdgcn_s_setprio(0); } while (0)
; #define PG8_WAIT_V(n) asm volatile("s_waitcnt vmcnt(" #n ")" ::: "memory")
; #define PG8_WAIT_L(n) asm volatile("s_waitcnt lgkmcnt(" #n ")" ::: "memory")
; #define PG8_BAR __builtin_amdgcn_s_barrier()
; #define PG8_SCHED __builtin_amdgcn_sched_barrier(0)
; template <class Epi, class Sched, bool ALIGN_EPI = false, bool SP2 = false, bool RS = false, bool BPRE = false>
; __device__ __forceinline__ void gemm_phase(PG8_LAS unsigned char* lds, const Gemm g, const Sched& S, const Epi& E, const float* rs_ss = nullptr, PG8_LAS float* rs_tab = nullptr) {
;     ...
;         const char* nA = has_next ? (const char*)g.A + (size_t)nxt.pm * tstep : cA; const char* nB = has_next ? (const char*)g.Bt + (size_t)nxt.pn * tstep : cB;
;     ...
;             PG8_LDB(B0, 0, 0); PG8_LDB(B1, 0, 1); PG8_SCHED; PG8_LDA(At, 0, 0); PG8_STAGE(PG8_SA(1, 1), a1 + hstep, voffA);
;             PG8_WAIT_V(8); PG8_WAIT_L(0); PG8_BAR; PG8_MMA(0, 0, At, B0); PG8_MMA(0, 1, At, B1); PG8_BAR; PG8_SCHED;
;             PG8_LDA(At, 0, 1); PG8_STAGE(PG8_SB(0, 0), b2, voffB); PG8_STAGE(PG8_SB(0, 1), b2 + hstep, voffB); PG8_STAGE(PG8_SA(0, 0), a2, voffA);
;             PG8_WAIT_V(8); PG8_WAIT_L(0); PG8_BAR; PG8_MMA(1, 0, At, B0); PG8_MMA(1, 1, At, B1); PG8_BAR; PG8_SCHED;
.LBB0_195:
	s_ashr_i32 s19, s18, 31
	s_lshl_b64 s[20:21], s[18:19], 20
	s_add_u32 s20, s30, s20
	s_addc_u32 s21, s31, s21
	s_and_b64 s[44:45], s[6:7], exec
	s_cselect_b32 s5, s21, s57
	s_cselect_b32 s19, s20, s56
	s_ashr_i32 s17, s16, 31
	s_lshl_b64 s[44:45], s[16:17], 20
	s_add_u32 s44, s24, s44
	s_addc_u32 s45, s25, s45
	s_and_b64 s[60:61], s[6:7], exec
	s_cselect_b32 s17, s45, s59
	s_cselect_b32 s47, s44, s58
	s_add_u32 s56, s56, 0x84000
	s_addc_u32 s57, s57, 0
	s_add_u32 s87, s58, 0x8000
	s_addc_u32 s88, s59, 0
	s_mov_b32 s89, -2
	s_waitcnt lgkmcnt(0)
	ds_read_b128 v[130:133], v161
	ds_read_b128 v[134:137], v161 offset:1024
	s_add_u32 s58, s56, 0xfff84000
	s_addc_u32 s59, s57, -1
	ds_read_b128 v[152:155], v161 offset:2048
	ds_read_b128 v[156:159], v161 offset:3072
	s_cmp_eq_u32 s89, 28
	s_cselect_b32 s70, s19, s58
	ds_read_b128 v[166:169], v162
	ds_read_b128 v[170:173], v162 offset:1024
	s_cselect_b32 s71, s5, s59
	s_cselect_b32 s60, s47, s87
	ds_read_b128 v[174:177], v162 offset:2048
	ds_read_b128 v[182:185], v162 offset:3072
	s_cselect_b32 s61, s17, s88
	s_add_u32 s58, s70, 0x4000
	ds_read_b128 v[188:191], v163
	ds_read_b128 v[192:195], v163 offset:1024
	s_addc_u32 s59, s71, 0
	ds_read_b128 v[196:199], v163 offset:2048
	ds_read_b128 v[200:203], v163 offset:3072
	v_lshl_add_u64 v[178:179], s[56:57], 0, v[138:139]
	s_add_i32 m0, s72, 0xc000
	ds_read_b128 v[204:207], v163 offset:4096
	ds_read_b128 v[208:211], v163 offset:5120
	global_load_lds_dwordx4 v[178:179], off
	v_lshl_add_u64 v[178:179], s[56:57], 0, v[146:147]
	ds_read_b128 v[212:215], v163 offset:6144
	ds_read_b128 v[216:219], v163 offset:7168
	s_add_i32 m0, s72, 0xe000
	s_nop 0
	global_load_lds_dwordx4 v[178:179], off
	s_waitcnt vmcnt(8)
	s_waitcnt lgkmcnt(0)
	s_barrier
	s_setprio 1
	s_waitcnt lgkmcnt(0)
	v_mfma_f32_16x16x32_bf16 v[126:129], v[130:133], v[188:191], 0
	v_mfma_f32_16x16x32_bf16 v[126:129], v[134:137], v[192:195], v[126:129]
	v_mfma_f32_16x16x32_bf16 v[122:125], v[156:159], v[192:195], 0
	v_mfma_f32_16x16x32_bf16 v[122:125], v[152:155], v[188:191], v[122:125]
	v_mfma_f32_16x16x32_bf16 v[106:109], v[152:155], v[196:199], 0
	v_mfma_f32_16x16x32_bf16 v[106:109], v[156:159], v[200:203], v[106:109]
	v_mfma_f32_16x16x32_bf16 v[110:113], v[134:137], v[200:203], 0
	v_mfma_f32_16x16x32_bf16 v[110:113], v[130:133], v[196:199], v[110:113]
	v_mfma_f32_16x16x32_bf16 v[94:97], v[130:133], v[204:207], 0
	v_mfma_f32_16x16x32_bf16 v[94:97], v[134:137], v[208:211], v[94:97]
	v_mfma_f32_16x16x32_bf16 v[90:93], v[156:159], v[208:211], 0
	v_mfma_f32_16x16x32_bf16 v[90:93], v[152:155], v[204:207], v[90:93]
	v_mfma_f32_16x16x32_bf16 v[74:77], v[152:155], v[212:215], 0
	v_mfma_f32_16x16x32_bf16 v[74:77], v[156:159], v[216:219], v[74:77]
	v_mfma_f32_16x16x32_bf16 v[78:81], v[134:137], v[216:219], 0
	v_mfma_f32_16x16x32_bf16 v[78:81], v[130:133], v[212:215], v[78:81]
	s_setprio 0
	s_setprio 1
	v_mfma_f32_16x16x32_bf16 v[70:73], v[166:169], v[212:215], 0
	v_mfma_f32_16x16x32_bf16 v[70:73], v[170:173], v[216:219], v[70:73]
	v_mfma_f32_16x16x32_bf16 v[66:69], v[182:185], v[216:219], 0
	v_mfma_f32_16x16x32_bf16 v[66:69], v[174:177], v[212:215], v[66:69]
	v_mfma_f32_16x16x32_bf16 v[82:85], v[174:177], v[204:207], 0
	v_mfma_f32_16x16x32_bf16 v[82:85], v[182:185], v[208:211], v[82:85]
	v_mfma_f32_16x16x32_bf16 v[86:89], v[170:173], v[208:211], 0
	v_mfma_f32_16x16x32_bf16 v[86:89], v[166:169], v[204:207], v[86:89]
	v_mfma_f32_16x16x32_bf16 v[102:105], v[166:169], v[196:199], 0
	v_mfma_f32_16x16x32_bf16 v[102:105], v[170:173], v[200:203], v[102:105]
	v_mfma_f32_16x16x32_bf16 v[98:101], v[182:185], v[200:203], 0
	v_mfma_f32_16x16x32_bf16 v[98:101], v[174:177], v[196:199], v[98:101]
	v_mfma_f32_16x16x32_bf16 v[114:117], v[174:177], v[188:191], 0
	v_mfma_f32_16x16x32_bf16 v[114:117], v[182:185], v[192:195], v[114:117]
	v_mfma_f32_16x16x32_bf16 v[118:121], v[170:173], v[192:195], 0
	v_mfma_f32_16x16x32_bf16 v[118:121], v[166:169], v[188:191], v[118:121]
	s_setprio 0
	s_barrier
	ds_read_b128 v[188:191], v163 offset:16384
	ds_read_b128 v[192:195], v163 offset:17408
	s_add_i32 s90, s83, s15
	v_lshl_add_u64 v[178:179], s[60:61], 0, v[138:139]
	s_mov_b32 m0, s90
	s_nop 0
	global_load_lds_dwordx4 v[178:179], off
	ds_read_b128 v[196:199], v163 offset:18432
	ds_read_b128 v[200:203], v163 offset:19456
	s_add_i32 m0, s90, 0x2000
	s_add_u32 s90, s60, 0x80000
	v_lshl_add_u64 v[178:179], s[60:61], 0, v[140:141]
	s_addc_u32 s91, s61, 0
	s_add_i32 s92, s86, s15
	global_load_lds_dwordx4 v[178:179], off
	ds_read_b128 v[204:207], v163 offset:20480
	ds_read_b128 v[208:211], v163 offset:21504
	v_lshl_add_u64 v[178:179], s[90:91], 0, v[138:139]
	s_mov_b32 m0, s92
	s_nop 0
	global_load_lds_dwordx4 v[178:179], off
	v_lshl_add_u64 v[178:179], s[90:91], 0, v[140:141]
	s_add_i32 m0, s92, 0x2000
	s_nop 0
	global_load_lds_dwordx4 v[178:179], off
	ds_read_b128 v[212:215], v163 offset:22528
	ds_read_b128 v[216:219], v163 offset:23552
	v_lshl_add_u64 v[178:179], s[70:71], 0, v[138:139]
	s_mov_b32 m0, s72
	s_nop 0
	global_load_lds_dwordx4 v[178:179], off
	v_lshl_add_u64 v[178:179], s[70:71], 0, v[140:141]
	s_mov_b32 m0, s73
	s_nop 0
	global_load_lds_dwordx4 v[178:179], off
	s_waitcnt vmcnt(8)
	s_waitcnt lgkmcnt(0)
	s_barrier
; #define PG8_STAGE(bufoff, gbase, voff) do { _Pragma("unroll") for (int _i = 0; _i < 2; ++_i) \
;         __builtin_amdgcn_global_load_lds((const unsigned*)((const char*)(gbase) + (voff)[_i]), (PG8_LAS unsigned*)(lds + (bufoff) + ldsw + _i * 8192), 16, 0, 0); } while (0)
; #define PG8_LDA(dst, b, h) do { _Pragma("unroll") for (int m = 0; m < 4; ++m) _Pragma("unroll") for (int k = 0; k < 2; ++k) dst[m][k] = *(const PG8_LAS bf16x8*)(lds + PG8_SA(b, h) + aoff + m * 2048 + k * 1024); } while (0)
; #define PG8_LDB(dst, b, h) do { _Pragma("unroll") for (int n = 0; n < 2; ++n) _Pragma("unroll") for (int k = 0; k < 2; ++k) dst[n][k] = *(const PG8_LAS bf16x8*)(lds + PG8_SB(b, h) + boff + n * 2048 + k * 1024); } while (0)
; #define PG8_MMA(ai, bj, At, Bt) do { __builtin_amdgcn_s_setprio(1); _Pragma("unroll") for (int m = 0; m < 4; ++m) _Pragma("unroll") for (int n = 0; n < 2; ++n) _Pragma("unroll") for (int k = 0; k < 2; ++k) \
;         acc[ai][bj][m][n] = __builtin_amdgcn_mfma_f32_16x16x32_bf16(Bt[n][k], At[m][k], acc[ai][bj][m][n], 0, 0, 0); __builtin_amdgcn_s_setprio(0); } while (0)
; #define PG8_WAIT_V(n) asm volatile("s_waitcnt vmcnt(" #n ")" ::: "memory")
; #define PG8_WAIT_L(n) asm volatile("s_waitcnt lgkmcnt(" #n ")" ::: "memory")
; #define PG8_BAR __builtin_amdgcn_s_barrier()
; #define PG8_SCHED __builtin_amdgcn_sched_barrier(0)
; template <class Epi, class Sched, bool ALIGN_EPI = false, bool SP2 = false, bool RS = false, bool BPRE = false>
; __device__ __forceinline__ void gemm_phase(PG8_LAS unsigned char* lds, const Gemm g, const Sched& S, const Epi& E, const float* rs_ss = nullptr, PG8_LAS float* rs_tab = nullptr) {
;     ...
;             PG8_WAIT_V(8); PG8_WAIT_L(0); PG8_BAR; PG8_MMA(1, 0, At, B0); PG8_MMA(1, 1, At, B1); PG8_BAR; PG8_SCHED;
;             PG8_LDB(B0, 1, 0); PG8_LDB(B1, 1, 1); PG8_SCHED; PG8_LDA(At, 1, 0); PG8_STAGE(PG8_SA(0, 1), a2 + hstep, voffA);
;             PG8_WAIT_V(8); PG8_WAIT_L(0); PG8_BAR; PG8_MMA(0, 0, At, B0); PG8_MMA(0, 1, At, B1); PG8_BAR; PG8_SCHED;
	s_setprio 1
	s_waitcnt lgkmcnt(0)
	v_mfma_f32_16x16x32_bf16 v[62:65], v[130:133], v[188:191], 0
	v_mfma_f32_16x16x32_bf16 v[62:65], v[134:137], v[192:195], v[62:65]
	v_mfma_f32_16x16x32_bf16 v[58:61], v[156:159], v[192:195], 0
	v_mfma_f32_16x16x32_bf16 v[58:61], v[152:155], v[188:191], v[58:61]
	v_mfma_f32_16x16x32_bf16 v[42:45], v[152:155], v[196:199], 0
	v_mfma_f32_16x16x32_bf16 v[42:45], v[156:159], v[200:203], v[42:45]
	v_mfma_f32_16x16x32_bf16 v[46:49], v[134:137], v[200:203], 0
	v_mfma_f32_16x16x32_bf16 v[46:49], v[130:133], v[196:199], v[46:49]
	v_mfma_f32_16x16x32_bf16 v[30:33], v[130:133], v[204:207], 0
	v_mfma_f32_16x16x32_bf16 v[30:33], v[134:137], v[208:211], v[30:33]
	v_mfma_f32_16x16x32_bf16 v[26:29], v[156:159], v[208:211], 0
	v_mfma_f32_16x16x32_bf16 v[26:29], v[152:155], v[204:207], v[26:29]
	v_mfma_f32_16x16x32_bf16 v[10:13], v[152:155], v[212:215], 0
	v_mfma_f32_16x16x32_bf16 v[10:13], v[156:159], v[216:219], v[10:13]
	v_mfma_f32_16x16x32_bf16 v[14:17], v[134:137], v[216:219], 0
	v_mfma_f32_16x16x32_bf16 v[14:17], v[130:133], v[212:215], v[14:17]
	s_setprio 0
	s_setprio 1
	v_mfma_f32_16x16x32_bf16 v[6:9], v[166:169], v[212:215], 0
	v_mfma_f32_16x16x32_bf16 v[6:9], v[170:173], v[216:219], v[6:9]
	v_mfma_f32_16x16x32_bf16 v[2:5], v[182:185], v[216:219], 0
	v_mfma_f32_16x16x32_bf16 v[2:5], v[174:177], v[212:215], v[2:5]
	v_mfma_f32_16x16x32_bf16 v[18:21], v[174:177], v[204:207], 0
	v_mfma_f32_16x16x32_bf16 v[18:21], v[182:185], v[208:211], v[18:21]
	v_mfma_f32_16x16x32_bf16 v[22:25], v[170:173], v[208:211], 0
	v_mfma_f32_16x16x32_bf16 v[22:25], v[166:169], v[204:207], v[22:25]
	v_mfma_f32_16x16x32_bf16 v[38:41], v[166:169], v[196:199], 0
	v_mfma_f32_16x16x32_bf16 v[38:41], v[170:173], v[200:203], v[38:41]
	v_mfma_f32_16x16x32_bf16 v[34:37], v[182:185], v[200:203], 0
	v_mfma_f32_16x16x32_bf16 v[34:37], v[174:177], v[196:199], v[34:37]
	v_mfma_f32_16x16x32_bf16 v[50:53], v[174:177], v[188:191], 0
	v_mfma_f32_16x16x32_bf16 v[50:53], v[182:185], v[192:195], v[50:53]
	v_mfma_f32_16x16x32_bf16 v[54:57], v[170:173], v[192:195], 0
	v_mfma_f32_16x16x32_bf16 v[54:57], v[166:169], v[188:191], v[54:57]
	s_setprio 0
	s_barrier
	s_add_i32 s90, 0, 0x18000
	v_add_u32_e32 v143, s90, v160
	s_add_i32 s91, 0, 0x1c000
	ds_read_b128 v[130:133], v143
	ds_read_b128 v[134:137], v143 offset:1024
	ds_read_b128 v[152:155], v143 offset:2048
	ds_read_b128 v[156:159], v143 offset:3072
	s_add_u32 s70, s70, 0x80000
	v_add_u32_e32 v143, s91, v160
	ds_read_b128 v[166:169], v143
	ds_read_b128 v[170:173], v143 offset:1024
	s_addc_u32 s71, s71, 0
	ds_read_b128 v[174:177], v143 offset:2048
	ds_read_b128 v[182:185], v143 offset:3072
	s_mov_b32 m0, s74
	ds_read_b128 v[188:191], v163 offset:32768
	ds_read_b128 v[192:195], v163 offset:33792
	v_lshl_add_u64 v[178:179], s[70:71], 0, v[138:139]
	ds_read_b128 v[196:199], v163 offset:34816
	ds_read_b128 v[200:203], v163 offset:35840
	global_load_lds_dwordx4 v[178:179], off
	ds_read_b128 v[204:207], v163 offset:36864
	ds_read_b128 v[208:211], v163 offset:37888
	v_lshl_add_u64 v[178:179], s[70:71], 0, v[140:141]
	ds_read_b128 v[212:215], v163 offset:38912
	ds_read_b128 v[216:219], v163 offset:39936
	s_mov_b32 m0, s75
	s_nop 0
	global_load_lds_dwordx4 v[178:179], off
	s_waitcnt vmcnt(8)
	s_waitcnt lgkmcnt(0)
	s_barrier
	s_setprio 1
	s_waitcnt lgkmcnt(0)
	v_mfma_f32_16x16x32_bf16 v[126:129], v[130:133], v[188:191], v[126:129]
	v_mfma_f32_16x16x32_bf16 v[126:129], v[134:137], v[192:195], v[126:129]
	v_mfma_f32_16x16x32_bf16 v[122:125], v[156:159], v[192:195], v[122:125]
	v_mfma_f32_16x16x32_bf16 v[122:125], v[152:155], v[188:191], v[122:125]
	v_mfma_f32_16x16x32_bf16 v[106:109], v[152:155], v[196:199], v[106:109]
	v_mfma_f32_16x16x32_bf16 v[106:109], v[156:159], v[200:203], v[106:109]
	v_mfma_f32_16x16x32_bf16 v[110:113], v[134:137], v[200:203], v[110:113]
	v_mfma_f32_16x16x32_bf16 v[110:113], v[130:133], v[196:199], v[110:113]
	v_mfma_f32_16x16x32_bf16 v[94:97], v[130:133], v[204:207], v[94:97]
	v_mfma_f32_16x16x32_bf16 v[94:97], v[134:137], v[208:211], v[94:97]
	v_mfma_f32_16x16x32_bf16 v[90:93], v[156:159], v[208:211], v[90:93]
	v_mfma_f32_16x16x32_bf16 v[90:93], v[152:155], v[204:207], v[90:93]
	v_mfma_f32_16x16x32_bf16 v[74:77], v[152:155], v[212:215], v[74:77]
	v_mfma_f32_16x16x32_bf16 v[74:77], v[156:159], v[216:219], v[74:77]
	v_mfma_f32_16x16x32_bf16 v[78:81], v[134:137], v[216:219], v[78:81]
	v_mfma_f32_16x16x32_bf16 v[78:81], v[130:133], v[212:215], v[78:81]
	s_setprio 0
	s_setprio 1
	v_mfma_f32_16x16x32_bf16 v[70:73], v[166:169], v[212:215], v[70:73]
	v_mfma_f32_16x16x32_bf16 v[70:73], v[170:173], v[216:219], v[70:73]
	v_mfma_f32_16x16x32_bf16 v[66:69], v[182:185], v[216:219], v[66:69]
	v_mfma_f32_16x16x32_bf16 v[66:69], v[174:177], v[212:215], v[66:69]
	v_mfma_f32_16x16x32_bf16 v[82:85], v[174:177], v[204:207], v[82:85]
	v_mfma_f32_16x16x32_bf16 v[82:85], v[182:185], v[208:211], v[82:85]
	v_mfma_f32_16x16x32_bf16 v[86:89], v[170:173], v[208:211], v[86:89]
	v_mfma_f32_16x16x32_bf16 v[86:89], v[166:169], v[204:207], v[86:89]
	v_mfma_f32_16x16x32_bf16 v[102:105], v[166:169], v[196:199], v[102:105]
	v_mfma_f32_16x16x32_bf16 v[102:105], v[170:173], v[200:203], v[102:105]
	v_mfma_f32_16x16x32_bf16 v[98:101], v[182:185], v[200:203], v[98:101]
	v_mfma_f32_16x16x32_bf16 v[98:101], v[174:177], v[196:199], v[98:101]
	v_mfma_f32_16x16x32_bf16 v[114:117], v[174:177], v[188:191], v[114:117]
	v_mfma_f32_16x16x32_bf16 v[114:117], v[182:185], v[192:195], v[114:117]
	v_mfma_f32_16x16x32_bf16 v[118:121], v[170:173], v[192:195], v[118:121]
	v_mfma_f32_16x16x32_bf16 v[118:121], v[166:169], v[188:191], v[118:121]
	s_setprio 0
	s_barrier
; #define PG8_STAGE(bufoff, gbase, voff) do { _Pragma("unroll") for (int _i = 0; _i < 2; ++_i) \
;         __builtin_amdgcn_global_load_lds((const unsigned*)((const char*)(gbase) + (voff)[_i]), (PG8_LAS unsigned*)(lds + (bufoff) + ldsw + _i * 8192), 16, 0, 0); } while (0)
; #define PG8_LDA(dst, b, h) do { _Pragma("unroll") for (int m = 0; m < 4; ++m) _Pragma("unroll") for (int k = 0; k < 2; ++k) dst[m][k] = *(const PG8_LAS bf16x8*)(lds + PG8_SA(b, h) + aoff + m * 2048 + k * 1024); } while (0)
; #define PG8_LDB(dst, b, h) do { _Pragma("unroll") for (int n = 0; n < 2; ++n) _Pragma("unroll") for (int k = 0; k < 2; ++k) dst[n][k] = *(const PG8_LAS bf16x8*)(lds + PG8_SB(b, h) + boff + n * 2048 + k * 1024); } while (0)
; template <class Epi, class Sched, bool ALIGN_EPI = false, bool SP2 = false, bool RS = false, bool BPRE = false>
; __device__ __forceinline__ void gemm_phase(PG8_LAS unsigned char* lds, const Gemm g, const Sched& S, const Epi& E, const float* rs_ss = nullptr, PG8_LAS float* rs_tab = nullptr) {
;     ...
;             const char* a1 = cA + (size_t)(t + 1) * kstep;
;             const char* a2 = last ? nA : cA + (size_t)(t + 2) * kstep; const char* b2 = last ? nB : cB + (size_t)(t + 2) * kstep;
;             const char* a3 = a2 + kstep; const char* b3 = b2 + kstep;
;             if (last && has_next) S.a_ready(nxt);
;             if constexpr (SP2) {
;             PG8_LDB(B0, 0, 0); PG8_LDB(B1, 0, 1); PG8_SCHED; PG8_LDA(At, 0, 0); PG8_STAGE(PG8_SA(1, 1), a1 + hstep, voffA);
;             PG8_WAIT_V(8); PG8_WAIT_L(0); PG8_BAR; PG8_MMA(0, 0, At, B0); PG8_MMA(0, 1, At, B1); PG8_BAR; PG8_SCHED;
;             PG8_LDA(At, 0, 1); PG8_STAGE(PG8_SB(0, 0), b2, voffB); PG8_STAGE(PG8_SB(0, 1), b2 + hstep, voffB); PG8_STAGE(PG8_SA(0, 0), a2, voffA);
;             PG8_WAIT_V(8); PG8_WAIT_L(0); PG8_BAR; PG8_MMA(1, 0, At, B0); PG8_MMA(1, 1, At, B1); PG8_BAR; PG8_SCHED;
;             PG8_LDB(B0, 1, 0); PG8_LDB(B1, 1, 1); PG8_SCHED; PG8_LDA(At, 1, 0); PG8_STAGE(PG8_SA(0, 1), a2 + hstep, voffA);
;             PG8_WAIT_V(8); PG8_WAIT_L(0); PG8_BAR; PG8_MMA(0, 0, At, B0); PG8_MMA(0, 1, At, B1); PG8_BAR; PG8_SCHED;
;             PG8_LDA(At, 1, 1); PG8_STAGE(PG8_SB(1, 0), b3, voffB); PG8_STAGE(PG8_SB(1, 1), b3 + hstep, voffB); PG8_STAGE(PG8_SA(1, 0), a3, voffA);
;             PG8_WAIT_V(8); PG8_WAIT_L(0); PG8_BAR; PG8_MMA(1, 0, At, B0); PG8_MMA(1, 1, At, B1); PG8_BAR; PG8_SCHED;
	ds_read_b128 v[188:191], v163 offset:49152
	ds_read_b128 v[192:195], v163 offset:50176
	s_add_u32 s70, s60, 0x4000
	s_addc_u32 s71, s61, 0
	s_add_i32 s90, s90, s15
	v_lshl_add_u64 v[178:179], s[70:71], 0, v[138:139]
	s_mov_b32 m0, s90
	ds_read_b128 v[196:199], v163 offset:51200
	ds_read_b128 v[200:203], v163 offset:52224
	global_load_lds_dwordx4 v[178:179], off
	s_add_i32 m0, s90, 0x2000
	s_add_u32 s60, s60, 0x84000
	v_lshl_add_u64 v[178:179], s[70:71], 0, v[140:141]
	s_addc_u32 s61, s61, 0
	s_add_i32 s70, s91, s15
	ds_read_b128 v[204:207], v163 offset:53248
	ds_read_b128 v[208:211], v163 offset:54272
	global_load_lds_dwordx4 v[178:179], off
	v_lshl_add_u64 v[178:179], s[60:61], 0, v[138:139]
	s_mov_b32 m0, s70
	s_nop 0
	global_load_lds_dwordx4 v[178:179], off
	v_lshl_add_u64 v[178:179], s[60:61], 0, v[140:141]
	s_add_i32 m0, s70, 0x2000
	ds_read_b128 v[212:215], v163 offset:55296
	ds_read_b128 v[216:219], v163 offset:56320
	global_load_lds_dwordx4 v[178:179], off
	v_lshl_add_u64 v[178:179], s[58:59], 0, v[138:139]
	s_mov_b32 m0, s79
	s_nop 0
	global_load_lds_dwordx4 v[178:179], off
	v_lshl_add_u64 v[178:179], s[58:59], 0, v[140:141]
	s_mov_b32 m0, s80
	s_nop 0
	global_load_lds_dwordx4 v[178:179], off
	s_waitcnt vmcnt(8)
	s_waitcnt lgkmcnt(0)
	s_barrier
	s_setprio 1
	s_waitcnt lgkmcnt(0)
	v_mfma_f32_16x16x32_bf16 v[62:65], v[130:133], v[188:191], v[62:65]
	v_mfma_f32_16x16x32_bf16 v[62:65], v[134:137], v[192:195], v[62:65]
	v_mfma_f32_16x16x32_bf16 v[58:61], v[156:159], v[192:195], v[58:61]
	v_mfma_f32_16x16x32_bf16 v[58:61], v[152:155], v[188:191], v[58:61]
	v_mfma_f32_16x16x32_bf16 v[42:45], v[152:155], v[196:199], v[42:45]
	v_mfma_f32_16x16x32_bf16 v[42:45], v[156:159], v[200:203], v[42:45]
	v_mfma_f32_16x16x32_bf16 v[46:49], v[134:137], v[200:203], v[46:49]
	v_mfma_f32_16x16x32_bf16 v[46:49], v[130:133], v[196:199], v[46:49]
	v_mfma_f32_16x16x32_bf16 v[30:33], v[130:133], v[204:207], v[30:33]
	v_mfma_f32_16x16x32_bf16 v[30:33], v[134:137], v[208:211], v[30:33]
	v_mfma_f32_16x16x32_bf16 v[26:29], v[156:159], v[208:211], v[26:29]
	v_mfma_f32_16x16x32_bf16 v[26:29], v[152:155], v[204:207], v[26:29]
	v_mfma_f32_16x16x32_bf16 v[10:13], v[152:155], v[212:215], v[10:13]
	v_mfma_f32_16x16x32_bf16 v[10:13], v[156:159], v[216:219], v[10:13]
	v_mfma_f32_16x16x32_bf16 v[14:17], v[134:137], v[216:219], v[14:17]
	v_mfma_f32_16x16x32_bf16 v[14:17], v[130:133], v[212:215], v[14:17]
	s_setprio 0
	s_setprio 1
	v_mfma_f32_16x16x32_bf16 v[6:9], v[166:169], v[212:215], v[6:9]
	v_mfma_f32_16x16x32_bf16 v[6:9], v[170:173], v[216:219], v[6:9]
	v_mfma_f32_16x16x32_bf16 v[2:5], v[182:185], v[216:219], v[2:5]
	v_mfma_f32_16x16x32_bf16 v[2:5], v[174:177], v[212:215], v[2:5]
	v_mfma_f32_16x16x32_bf16 v[18:21], v[174:177], v[204:207], v[18:21]
	v_mfma_f32_16x16x32_bf16 v[18:21], v[182:185], v[208:211], v[18:21]
	v_mfma_f32_16x16x32_bf16 v[22:25], v[170:173], v[208:211], v[22:25]
	v_mfma_f32_16x16x32_bf16 v[22:25], v[166:169], v[204:207], v[22:25]
	v_mfma_f32_16x16x32_bf16 v[38:41], v[166:169], v[196:199], v[38:41]
	v_mfma_f32_16x16x32_bf16 v[38:41], v[170:173], v[200:203], v[38:41]
	v_mfma_f32_16x16x32_bf16 v[34:37], v[182:185], v[200:203], v[34:37]
	v_mfma_f32_16x16x32_bf16 v[34:37], v[174:177], v[196:199], v[34:37]
	v_mfma_f32_16x16x32_bf16 v[50:53], v[174:177], v[188:191], v[50:53]
	v_mfma_f32_16x16x32_bf16 v[50:53], v[182:185], v[192:195], v[50:53]
	v_mfma_f32_16x16x32_bf16 v[54:57], v[170:173], v[192:195], v[54:57]
	v_mfma_f32_16x16x32_bf16 v[54:57], v[166:169], v[188:191], v[54:57]
	s_setprio 0
	s_barrier
	s_add_i32 s89, s89, 2
	s_add_u32 s56, s56, 0x8000
	s_addc_u32 s57, s57, 0
	s_add_u32 s87, s87, 0x8000
	s_addc_u32 s88, s88, 0
.LBB0_196:
	ds_read_b128 v[130:133], v161
	ds_read_b128 v[134:137], v161 offset:1024
	s_add_u32 s58, s56, 0xfff84000
	s_addc_u32 s59, s57, -1
	ds_read_b128 v[152:155], v161 offset:2048
	ds_read_b128 v[156:159], v161 offset:3072
	s_cmp_eq_u32 s89, 28
	s_cselect_b32 s70, s19, s58
	ds_read_b128 v[166:169], v162
	ds_read_b128 v[170:173], v162 offset:1024
	s_cselect_b32 s71, s5, s59
	s_cselect_b32 s60, s47, s87
	ds_read_b128 v[174:177], v162 offset:2048
	ds_read_b128 v[182:185], v162 offset:3072
	s_cselect_b32 s61, s17, s88
	s_add_u32 s58, s70, 0x4000
	ds_read_b128 v[188:191], v163
	ds_read_b128 v[192:195], v163 offset:1024
	s_addc_u32 s59, s71, 0
	ds_read_b128 v[196:199], v163 offset:2048
	ds_read_b128 v[200:203], v163 offset:3072
	v_lshl_add_u64 v[178:179], s[56:57], 0, v[138:139]
	s_add_i32 m0, s72, 0xc000
	ds_read_b128 v[204:207], v163 offset:4096
	ds_read_b128 v[208:211], v163 offset:5120
	global_load_lds_dwordx4 v[178:179], off
	v_lshl_add_u64 v[178:179], s[56:57], 0, v[146:147]
	ds_read_b128 v[212:215], v163 offset:6144
	ds_read_b128 v[216:219], v163 offset:7168
	s_add_i32 m0, s72, 0xe000
	s_nop 0
	global_load_lds_dwordx4 v[178:179], off
	s_waitcnt vmcnt(8)
	s_waitcnt lgkmcnt(0)
	s_barrier
; #define PG8_STAGE(bufoff, gbase, voff) do { _Pragma("unroll") for (int _i = 0; _i < 2; ++_i) \
;         __builtin_amdgcn_global_load_lds((const unsigned*)((const char*)(gbase) + (voff)[_i]), (PG8_LAS unsigned*)(lds + (bufoff) + ldsw + _i * 8192), 16, 0, 0); } while (0)
; #define PG8_LDA(dst, b, h) do { _Pragma("unroll") for (int m = 0; m < 4; ++m) _Pragma("unroll") for (int k = 0; k < 2; ++k) dst[m][k] = *(const PG8_LAS bf16x8*)(lds + PG8_SA(b, h) + aoff + m * 2048 + k * 1024); } while (0)
; #define PG8_MMA(ai, bj, At, Bt) do { __builtin_amdgcn_s_setprio(1); _Pragma("unroll") for (int m = 0; m < 4; ++m) _Pragma("unroll") for (int n = 0; n < 2; ++n) _Pragma("unroll") for (int k = 0; k < 2; ++k) \
;         acc[ai][bj][m][n] = __builtin_amdgcn_mfma_f32_16x16x32_bf16(Bt[n][k], At[m][k], acc[ai][bj][m][n], 0, 0, 0); __builtin_amdgcn_s_setprio(0); } while (0)
; #define PG8_WAIT_V(n) asm volatile("s_waitcnt vmcnt(" #n ")" ::: "memory")
; #define PG8_WAIT_L(n) asm volatile("s_waitcnt lgkmcnt(" #n ")" ::: "memory")
; #define PG8_BAR __builtin_amdgcn_s_barrier()
; #define PG8_SCHED __builtin_amdgcn_sched_barrier(0)
; template <class Epi, class Sched, bool ALIGN_EPI = false, bool SP2 = false, bool RS = false, bool BPRE = false>
; __device__ __forceinline__ void gemm_phase(PG8_LAS unsigned char* lds, const Gemm g, const Sched& S, const Epi& E, const float* rs_ss = nullptr, PG8_LAS float* rs_tab = nullptr) {
;     ...
;             PG8_WAIT_V(8); PG8_WAIT_L(0); PG8_BAR; PG8_MMA(0, 0, At, B0); PG8_MMA(0, 1, At, B1); PG8_BAR; PG8_SCHED;
;             PG8_LDA(At, 0, 1); PG8_STAGE(PG8_SB(0, 0), b2, voffB); PG8_STAGE(PG8_SB(0, 1), b2 + hstep, voffB); PG8_STAGE(PG8_SA(0, 0), a2, voffA);
;             PG8_WAIT_V(8); PG8_WAIT_L(0); PG8_BAR; PG8_MMA(1, 0, At, B0); PG8_MMA(1, 1, At, B1); PG8_BAR; PG8_SCHED;
	s_setprio 1
	s_waitcnt lgkmcnt(0)
	v_mfma_f32_16x16x32_bf16 v[126:129], v[130:133], v[188:191], v[126:129]
	v_mfma_f32_16x16x32_bf16 v[126:129], v[134:137], v[192:195], v[126:129]
	v_mfma_f32_16x16x32_bf16 v[122:125], v[156:159], v[192:195], v[122:125]
	v_mfma_f32_16x16x32_bf16 v[122:125], v[152:155], v[188:191], v[122:125]
	v_mfma_f32_16x16x32_bf16 v[106:109], v[152:155], v[196:199], v[106:109]
	v_mfma_f32_16x16x32_bf16 v[106:109], v[156:159], v[200:203], v[106:109]
	v_mfma_f32_16x16x32_bf16 v[110:113], v[134:137], v[200:203], v[110:113]
	v_mfma_f32_16x16x32_bf16 v[110:113], v[130:133], v[196:199], v[110:113]
	v_mfma_f32_16x16x32_bf16 v[94:97], v[130:133], v[204:207], v[94:97]
	v_mfma_f32_16x16x32_bf16 v[94:97], v[134:137], v[208:211], v[94:97]
	v_mfma_f32_16x16x32_bf16 v[90:93], v[156:159], v[208:211], v[90:93]
	v_mfma_f32_16x16x32_bf16 v[90:93], v[152:155], v[204:207], v[90:93]
	v_mfma_f32_16x16x32_bf16 v[74:77], v[152:155], v[212:215], v[74:77]
	v_mfma_f32_16x16x32_bf16 v[74:77], v[156:159], v[216:219], v[74:77]
	v_mfma_f32_16x16x32_bf16 v[78:81], v[134:137], v[216:219], v[78:81]
	v_mfma_f32_16x16x32_bf16 v[78:81], v[130:133], v[212:215], v[78:81]
	s_setprio 0
	s_setprio 1
	v_mfma_f32_16x16x32_bf16 v[70:73], v[166:169], v[212:215], v[70:73]
	v_mfma_f32_16x16x32_bf16 v[70:73], v[170:173], v[216:219], v[70:73]
	v_mfma_f32_16x16x32_bf16 v[66:69], v[182:185], v[216:219], v[66:69]
	v_mfma_f32_16x16x32_bf16 v[66:69], v[174:177], v[212:215], v[66:69]
	v_mfma_f32_16x16x32_bf16 v[82:85], v[174:177], v[204:207], v[82:85]
	v_mfma_f32_16x16x32_bf16 v[82:85], v[182:185], v[208:211], v[82:85]
	v_mfma_f32_16x16x32_bf16 v[86:89], v[170:173], v[208:211], v[86:89]
	v_mfma_f32_16x16x32_bf16 v[86:89], v[166:169], v[204:207], v[86:89]
	v_mfma_f32_16x16x32_bf16 v[102:105], v[166:169], v[196:199], v[102:105]
	v_mfma_f32_16x16x32_bf16 v[102:105], v[170:173], v[200:203], v[102:105]
	v_mfma_f32_16x16x32_bf16 v[98:101], v[182:185], v[200:203], v[98:101]
	v_mfma_f32_16x16x32_bf16 v[98:101], v[174:177], v[196:199], v[98:101]
	v_mfma_f32_16x16x32_bf16 v[114:117], v[174:177], v[188:191], v[114:117]
	v_mfma_f32_16x16x32_bf16 v[114:117], v[182:185], v[192:195], v[114:117]
	v_mfma_f32_16x16x32_bf16 v[118:121], v[170:173], v[192:195], v[118:121]
	v_mfma_f32_16x16x32_bf16 v[118:121], v[166:169], v[188:191], v[118:121]
	s_setprio 0
	s_barrier
	ds_read_b128 v[188:191], v163 offset:16384
	ds_read_b128 v[192:195], v163 offset:17408
	s_add_i32 s90, s83, s15
	v_lshl_add_u64 v[178:179], s[60:61], 0, v[138:139]
	s_mov_b32 m0, s90
	s_nop 0
	global_load_lds_dwordx4 v[178:179], off
	ds_read_b128 v[196:199], v163 offset:18432
	ds_read_b128 v[200:203], v163 offset:19456
	s_add_i32 m0, s90, 0x2000
	s_add_u32 s90, s60, 0x80000
	v_lshl_add_u64 v[178:179], s[60:61], 0, v[140:141]
	s_addc_u32 s91, s61, 0
	s_add_i32 s92, s86, s15
	global_load_lds_dwordx4 v[178:179], off
	ds_read_b128 v[204:207], v163 offset:20480
	ds_read_b128 v[208:211], v163 offset:21504
	v_lshl_add_u64 v[178:179], s[90:91], 0, v[138:139]
	s_mov_b32 m0, s92
	s_nop 0
	global_load_lds_dwordx4 v[178:179], off
	v_lshl_add_u64 v[178:179], s[90:91], 0, v[140:141]
	s_add_i32 m0, s92, 0x2000
	s_nop 0
	global_load_lds_dwordx4 v[178:179], off
	ds_read_b128 v[212:215], v163 offset:22528
	ds_read_b128 v[216:219], v163 offset:23552
	v_lshl_add_u64 v[178:179], s[70:71], 0, v[138:139]
	s_mov_b32 m0, s72
	s_nop 0
	global_load_lds_dwordx4 v[178:179], off
	v_lshl_add_u64 v[178:179], s[70:71], 0, v[140:141]
	s_mov_b32 m0, s73
	s_nop 0
	global_load_lds_dwordx4 v[178:179], off
	s_waitcnt vmcnt(8)
	s_waitcnt lgkmcnt(0)
	s_barrier
	s_setprio 1
	s_waitcnt lgkmcnt(0)
	v_mfma_f32_16x16x32_bf16 v[62:65], v[130:133], v[188:191], v[62:65]
	v_mfma_f32_16x16x32_bf16 v[62:65], v[134:137], v[192:195], v[62:65]
	v_mfma_f32_16x16x32_bf16 v[58:61], v[156:159], v[192:195], v[58:61]
	v_mfma_f32_16x16x32_bf16 v[58:61], v[152:155], v[188:191], v[58:61]
	v_mfma_f32_16x16x32_bf16 v[42:45], v[152:155], v[196:199], v[42:45]
	v_mfma_f32_16x16x32_bf16 v[42:45], v[156:159], v[200:203], v[42:45]
	v_mfma_f32_16x16x32_bf16 v[46:49], v[134:137], v[200:203], v[46:49]
	v_mfma_f32_16x16x32_bf16 v[46:49], v[130:133], v[196:199], v[46:49]
	v_mfma_f32_16x16x32_bf16 v[30:33], v[130:133], v[204:207], v[30:33]
	v_mfma_f32_16x16x32_bf16 v[30:33], v[134:137], v[208:211], v[30:33]
	v_mfma_f32_16x16x32_bf16 v[26:29], v[156:159], v[208:211], v[26:29]
	v_mfma_f32_16x16x32_bf16 v[26:29], v[152:155], v[204:207], v[26:29]
	v_mfma_f32_16x16x32_bf16 v[10:13], v[152:155], v[212:215], v[10:13]
	v_mfma_f32_16x16x32_bf16 v[10:13], v[156:159], v[216:219], v[10:13]
	v_mfma_f32_16x16x32_bf16 v[14:17], v[134:137], v[216:219], v[14:17]
	v_mfma_f32_16x16x32_bf16 v[14:17], v[130:133], v[212:215], v[14:17]
	s_setprio 0
	s_setprio 1
	v_mfma_f32_16x16x32_bf16 v[6:9], v[166:169], v[212:215], v[6:9]
	v_mfma_f32_16x16x32_bf16 v[6:9], v[170:173], v[216:219], v[6:9]
	v_mfma_f32_16x16x32_bf16 v[2:5], v[182:185], v[216:219], v[2:5]
	v_mfma_f32_16x16x32_bf16 v[2:5], v[174:177], v[212:215], v[2:5]
	v_mfma_f32_16x16x32_bf16 v[18:21], v[174:177], v[204:207], v[18:21]
	v_mfma_f32_16x16x32_bf16 v[18:21], v[182:185], v[208:211], v[18:21]
	v_mfma_f32_16x16x32_bf16 v[22:25], v[170:173], v[208:211], v[22:25]
	v_mfma_f32_16x16x32_bf16 v[22:25], v[166:169], v[204:207], v[22:25]
	v_mfma_f32_16x16x32_bf16 v[38:41], v[166:169], v[196:199], v[38:41]
	v_mfma_f32_16x16x32_bf16 v[38:41], v[170:173], v[200:203], v[38:41]
	v_mfma_f32_16x16x32_bf16 v[34:37], v[182:185], v[200:203], v[34:37]
	v_mfma_f32_16x16x32_bf16 v[34:37], v[174:177], v[196:199], v[34:37]
	v_mfma_f32_16x16x32_bf16 v[50:53], v[174:177], v[188:191], v[50:53]
	v_mfma_f32_16x16x32_bf16 v[50:53], v[182:185], v[192:195], v[50:53]
	v_mfma_f32_16x16x32_bf16 v[54:57], v[170:173], v[192:195], v[54:57]
	v_mfma_f32_16x16x32_bf16 v[54:57], v[166:169], v[188:191], v[54:57]
	s_setprio 0
	s_barrier
; #define PG8_STAGE(bufoff, gbase, voff) do { _Pragma("unroll") for (int _i = 0; _i < 2; ++_i) \
;         __builtin_amdgcn_global_load_lds((const unsigned*)((const char*)(gbase) + (voff)[_i]), (PG8_LAS unsigned*)(lds + (bufoff) + ldsw + _i * 8192), 16, 0, 0); } while (0)
; #define PG8_LDA(dst, b, h) do { _Pragma("unroll") for (int m = 0; m < 4; ++m) _Pragma("unroll") for (int k = 0; k < 2; ++k) dst[m][k] = *(const PG8_LAS bf16x8*)(lds + PG8_SA(b, h) + aoff + m * 2048 + k * 1024); } while (0)
; #define PG8_LDB(dst, b, h) do { _Pragma("unroll") for (int n = 0; n < 2; ++n) _Pragma("unroll") for (int k = 0; k < 2; ++k) dst[n][k] = *(const PG8_LAS bf16x8*)(lds + PG8_SB(b, h) + boff + n * 2048 + k * 1024); } while (0)
; #define PG8_MMA(ai, bj, At, Bt) do { __builtin_amdgcn_s_setprio(1); _Pragma("unroll") for (int m = 0; m < 4; ++m) _Pragma("unroll") for (int n = 0; n < 2; ++n) _Pragma("unroll") for (int k = 0; k < 2; ++k) \
;         acc[ai][bj][m][n] = __builtin_amdgcn_mfma_f32_16x16x32_bf16(Bt[n][k], At[m][k], acc[ai][bj][m][n], 0, 0, 0); __builtin_amdgcn_s_setprio(0); } while (0)
; #define PG8_WAIT_V(n) asm volatile("s_waitcnt vmcnt(" #n ")" ::: "memory")
; #define PG8_WAIT_L(n) asm volatile("s_waitcnt lgkmcnt(" #n ")" ::: "memory")
; #define PG8_BAR __builtin_amdgcn_s_barrier()
; #define PG8_SCHED __builtin_amdgcn_sched_barrier(0)
; template <class Epi, class Sched, bool ALIGN_EPI = false, bool SP2 = false, bool RS = false, bool BPRE = false>
; __device__ __forceinline__ void gemm_phase(PG8_LAS unsigned char* lds, const Gemm g, const Sched& S, const Epi& E, const float* rs_ss = nullptr, PG8_LAS float* rs_tab = nullptr) {
;     ...
;             PG8_LDB(B0, 1, 0); PG8_LDB(B1, 1, 1); PG8_SCHED; PG8_LDA(At, 1, 0); PG8_STAGE(PG8_SA(0, 1), a2 + hstep, voffA);
;             PG8_WAIT_V(8); PG8_WAIT_L(0); PG8_BAR; PG8_MMA(0, 0, At, B0); PG8_MMA(0, 1, At, B1); PG8_BAR; PG8_SCHED;
	s_add_i32 s90, 0, 0x18000
	v_add_u32_e32 v143, s90, v160
	s_add_i32 s91, 0, 0x1c000
	ds_read_b128 v[130:133], v143
	ds_read_b128 v[134:137], v143 offset:1024
	ds_read_b128 v[152:155], v143 offset:2048
	ds_read_b128 v[156:159], v143 offset:3072
	s_add_u32 s70, s70, 0x80000
	v_add_u32_e32 v143, s91, v160
	ds_read_b128 v[166:169], v143
	ds_read_b128 v[170:173], v143 offset:1024
	s_addc_u32 s71, s71, 0
	ds_read_b128 v[174:177], v143 offset:2048
	ds_read_b128 v[182:185], v143 offset:3072
	s_mov_b32 m0, s74
	ds_read_b128 v[188:191], v163 offset:32768
	ds_read_b128 v[192:195], v163 offset:33792
	v_lshl_add_u64 v[178:179], s[70:71], 0, v[138:139]
	ds_read_b128 v[196:199], v163 offset:34816
	ds_read_b128 v[200:203], v163 offset:35840
	global_load_lds_dwordx4 v[178:179], off
	ds_read_b128 v[204:207], v163 offset:36864
	ds_read_b128 v[208:211], v163 offset:37888
	v_lshl_add_u64 v[178:179], s[70:71], 0, v[140:141]
	ds_read_b128 v[212:215], v163 offset:38912
	ds_read_b128 v[216:219], v163 offset:39936
	s_mov_b32 m0, s75
	s_nop 0
	global_load_lds_dwordx4 v[178:179], off
	s_waitcnt vmcnt(8)
	s_waitcnt lgkmcnt(0)
	s_barrier
	s_setprio 1
	s_waitcnt lgkmcnt(0)
	v_mfma_f32_16x16x32_bf16 v[126:129], v[130:133], v[188:191], v[126:129]
	v_mfma_f32_16x16x32_bf16 v[126:129], v[134:137], v[192:195], v[126:129]
	v_mfma_f32_16x16x32_bf16 v[122:125], v[156:159], v[192:195], v[122:125]
	v_mfma_f32_16x16x32_bf16 v[122:125], v[152:155], v[188:191], v[122:125]
	v_mfma_f32_16x16x32_bf16 v[106:109], v[152:155], v[196:199], v[106:109]
	v_mfma_f32_16x16x32_bf16 v[106:109], v[156:159], v[200:203], v[106:109]
	v_mfma_f32_16x16x32_bf16 v[110:113], v[134:137], v[200:203], v[110:113]
	v_mfma_f32_16x16x32_bf16 v[110:113], v[130:133], v[196:199], v[110:113]
	v_mfma_f32_16x16x32_bf16 v[94:97], v[130:133], v[204:207], v[94:97]
	v_mfma_f32_16x16x32_bf16 v[94:97], v[134:137], v[208:211], v[94:97]
	v_mfma_f32_16x16x32_bf16 v[90:93], v[156:159], v[208:211], v[90:93]
	v_mfma_f32_16x16x32_bf16 v[90:93], v[152:155], v[204:207], v[90:93]
	v_mfma_f32_16x16x32_bf16 v[74:77], v[152:155], v[212:215], v[74:77]
	v_mfma_f32_16x16x32_bf16 v[74:77], v[156:159], v[216:219], v[74:77]
	v_mfma_f32_16x16x32_bf16 v[78:81], v[134:137], v[216:219], v[78:81]
	v_mfma_f32_16x16x32_bf16 v[78:81], v[130:133], v[212:215], v[78:81]
	s_setprio 0
	s_setprio 1
	v_mfma_f32_16x16x32_bf16 v[70:73], v[166:169], v[212:215], v[70:73]
	v_mfma_f32_16x16x32_bf16 v[70:73], v[170:173], v[216:219], v[70:73]
	v_mfma_f32_16x16x32_bf16 v[66:69], v[182:185], v[216:219], v[66:69]
	v_mfma_f32_16x16x32_bf16 v[66:69], v[174:177], v[212:215], v[66:69]
	v_mfma_f32_16x16x32_bf16 v[82:85], v[174:177], v[204:207], v[82:85]
	v_mfma_f32_16x16x32_bf16 v[82:85], v[182:185], v[208:211], v[82:85]
	v_mfma_f32_16x16x32_bf16 v[86:89], v[170:173], v[208:211], v[86:89]
	v_mfma_f32_16x16x32_bf16 v[86:89], v[166:169], v[204:207], v[86:89]
	v_mfma_f32_16x16x32_bf16 v[102:105], v[166:169], v[196:199], v[102:105]
	v_mfma_f32_16x16x32_bf16 v[102:105], v[170:173], v[200:203], v[102:105]
	v_mfma_f32_16x16x32_bf16 v[98:101], v[182:185], v[200:203], v[98:101]
	v_mfma_f32_16x16x32_bf16 v[98:101], v[174:177], v[196:199], v[98:101]
	v_mfma_f32_16x16x32_bf16 v[114:117], v[174:177], v[188:191], v[114:117]
	v_mfma_f32_16x16x32_bf16 v[114:117], v[182:185], v[192:195], v[114:117]
	v_mfma_f32_16x16x32_bf16 v[118:121], v[170:173], v[192:195], v[118:121]
	v_mfma_f32_16x16x32_bf16 v[118:121], v[166:169], v[188:191], v[118:121]
	s_setprio 0
	s_barrier
; #define PG8_STAGE(bufoff, gbase, voff) do { _Pragma("unroll") for (int _i = 0; _i < 2; ++_i) \
;         __builtin_amdgcn_global_load_lds((const unsigned*)((const char*)(gbase) + (voff)[_i]), (PG8_LAS unsigned*)(lds + (bufoff) + ldsw + _i * 8192), 16, 0, 0); } while (0)
; #define PG8_LDA(dst, b, h) do { _Pragma("unroll") for (int m = 0; m < 4; ++m) _Pragma("unroll") for (int k = 0; k < 2; ++k) dst[m][k] = *(const PG8_LAS bf16x8*)(lds + PG8_SA(b, h) + aoff + m * 2048 + k * 1024); } while (0)
; #define PG8_MMA(ai, bj, At, Bt) do { __builtin_amdgcn_s_setprio(1); _Pragma("unroll") for (int m = 0; m < 4; ++m) _Pragma("unroll") for (int n = 0; n < 2; ++n) _Pragma("unroll") for (int k = 0; k < 2; ++k) \
;         acc[ai][bj][m][n] = __builtin_amdgcn_mfma_f32_16x16x32_bf16(Bt[n][k], At[m][k], acc[ai][bj][m][n], 0, 0, 0); __builtin_amdgcn_s_setprio(0); } while (0)
; #define PG8_WAIT_V(n) asm volatile("s_waitcnt vmcnt(" #n ")" ::: "memory")
; #define PG8_WAIT_L(n) asm volatile("s_waitcnt lgkmcnt(" #n ")" ::: "memory")
; #define PG8_BAR __builtin_amdgcn_s_barrier()
; #define PG8_SCHED __builtin_amdgcn_sched_barrier(0)
; template <class Epi, class Sched, bool ALIGN_EPI = false, bool SP2 = false, bool RS = false, bool BPRE = false>
; __device__ __forceinline__ void gemm_phase(PG8_LAS unsigned char* lds, const Gemm g, const Sched& S, const Epi& E, const float* rs_ss = nullptr, PG8_LAS float* rs_tab = nullptr) {
;     ...
;         for (int t = 0; t < nt; t += 2) {
;     ...
;             PG8_LDA(At, 1, 1); PG8_STAGE(PG8_SB(1, 0), b3, voffB); PG8_STAGE(PG8_SB(1, 1), b3 + hstep, voffB); PG8_STAGE(PG8_SA(1, 0), a3, voffA);
;             PG8_WAIT_V(8); PG8_WAIT_L(0); PG8_BAR; PG8_MMA(1, 0, At, B0); PG8_MMA(1, 1, At, B1); PG8_BAR; PG8_SCHED;
	ds_read_b128 v[188:191], v163 offset:49152
	ds_read_b128 v[192:195], v163 offset:50176
	s_add_u32 s70, s60, 0x4000
	s_addc_u32 s71, s61, 0
	s_add_i32 s90, s90, s15
	v_lshl_add_u64 v[178:179], s[70:71], 0, v[138:139]
	s_mov_b32 m0, s90
	ds_read_b128 v[196:199], v163 offset:51200
	ds_read_b128 v[200:203], v163 offset:52224
	global_load_lds_dwordx4 v[178:179], off
	s_add_i32 m0, s90, 0x2000
	s_add_u32 s60, s60, 0x84000
	v_lshl_add_u64 v[178:179], s[70:71], 0, v[140:141]
	s_addc_u32 s61, s61, 0
	s_add_i32 s70, s91, s15
	ds_read_b128 v[204:207], v163 offset:53248
	ds_read_b128 v[208:211], v163 offset:54272
	global_load_lds_dwordx4 v[178:179], off
	v_lshl_add_u64 v[178:179], s[60:61], 0, v[138:139]
	s_mov_b32 m0, s70
	s_nop 0
	global_load_lds_dwordx4 v[178:179], off
	v_lshl_add_u64 v[178:179], s[60:61], 0, v[140:141]
	s_add_i32 m0, s70, 0x2000
	ds_read_b128 v[212:215], v163 offset:55296
	ds_read_b128 v[216:219], v163 offset:56320
	global_load_lds_dwordx4 v[178:179], off
	v_lshl_add_u64 v[178:179], s[58:59], 0, v[138:139]
	s_mov_b32 m0, s79
	s_nop 0
	global_load_lds_dwordx4 v[178:179], off
	v_lshl_add_u64 v[178:179], s[58:59], 0, v[140:141]
	s_mov_b32 m0, s80
	s_nop 0
	global_load_lds_dwordx4 v[178:179], off
	s_waitcnt vmcnt(8)
	s_waitcnt lgkmcnt(0)
	s_barrier
	s_setprio 1
	s_waitcnt lgkmcnt(0)
	v_mfma_f32_16x16x32_bf16 v[62:65], v[130:133], v[188:191], v[62:65]
	v_mfma_f32_16x16x32_bf16 v[62:65], v[134:137], v[192:195], v[62:65]
	v_mfma_f32_16x16x32_bf16 v[58:61], v[156:159], v[192:195], v[58:61]
	v_mfma_f32_16x16x32_bf16 v[58:61], v[152:155], v[188:191], v[58:61]
	v_mfma_f32_16x16x32_bf16 v[42:45], v[152:155], v[196:199], v[42:45]
	v_mfma_f32_16x16x32_bf16 v[42:45], v[156:159], v[200:203], v[42:45]
	v_mfma_f32_16x16x32_bf16 v[46:49], v[134:137], v[200:203], v[46:49]
	v_mfma_f32_16x16x32_bf16 v[46:49], v[130:133], v[196:199], v[46:49]
	v_mfma_f32_16x16x32_bf16 v[30:33], v[130:133], v[204:207], v[30:33]
	v_mfma_f32_16x16x32_bf16 v[30:33], v[134:137], v[208:211], v[30:33]
	v_mfma_f32_16x16x32_bf16 v[26:29], v[156:159], v[208:211], v[26:29]
	v_mfma_f32_16x16x32_bf16 v[26:29], v[152:155], v[204:207], v[26:29]
	v_mfma_f32_16x16x32_bf16 v[10:13], v[152:155], v[212:215], v[10:13]
	v_mfma_f32_16x16x32_bf16 v[10:13], v[156:159], v[216:219], v[10:13]
	v_mfma_f32_16x16x32_bf16 v[14:17], v[134:137], v[216:219], v[14:17]
	v_mfma_f32_16x16x32_bf16 v[14:17], v[130:133], v[212:215], v[14:17]
	s_setprio 0
	s_setprio 1
	v_mfma_f32_16x16x32_bf16 v[6:9], v[166:169], v[212:215], v[6:9]
	v_mfma_f32_16x16x32_bf16 v[6:9], v[170:173], v[216:219], v[6:9]
	v_mfma_f32_16x16x32_bf16 v[2:5], v[182:185], v[216:219], v[2:5]
	v_mfma_f32_16x16x32_bf16 v[2:5], v[174:177], v[212:215], v[2:5]
	v_mfma_f32_16x16x32_bf16 v[18:21], v[174:177], v[204:207], v[18:21]
	v_mfma_f32_16x16x32_bf16 v[18:21], v[182:185], v[208:211], v[18:21]
	v_mfma_f32_16x16x32_bf16 v[22:25], v[170:173], v[208:211], v[22:25]
	v_mfma_f32_16x16x32_bf16 v[22:25], v[166:169], v[204:207], v[22:25]
	v_mfma_f32_16x16x32_bf16 v[38:41], v[166:169], v[196:199], v[38:41]
	v_mfma_f32_16x16x32_bf16 v[38:41], v[170:173], v[200:203], v[38:41]
	v_mfma_f32_16x16x32_bf16 v[34:37], v[182:185], v[200:203], v[34:37]
	v_mfma_f32_16x16x32_bf16 v[34:37], v[174:177], v[196:199], v[34:37]
	v_mfma_f32_16x16x32_bf16 v[50:53], v[174:177], v[188:191], v[50:53]
	v_mfma_f32_16x16x32_bf16 v[50:53], v[182:185], v[192:195], v[50:53]
	v_mfma_f32_16x16x32_bf16 v[54:57], v[170:173], v[192:195], v[54:57]
	v_mfma_f32_16x16x32_bf16 v[54:57], v[166:169], v[188:191], v[54:57]
	s_setprio 0
	s_barrier
	s_add_i32 s89, s89, 2
	s_add_u32 s56, s56, 0x8000
	s_addc_u32 s57, s57, 0
	s_add_u32 s87, s87, 0x8000
	s_addc_u32 s88, s88, 0
	s_cmp_gt_u32 s89, 29
	s_cbranch_scc0 .LBB0_196
	s_and_b64 vcc, exec, s[12:13]
	s_cbranch_vccz .LBB0_199
	s_barrier
